# P0 input-to-bf16 stream: first 32 trips per thread run 4 at a time with 8 dwordx4 loads in flight (no bounds or source select needed there); original loop finishes the tail
# baseline (speedup 1.0000x reference)
.LBB0_57:
	s_mov_b32 s79, 0
	s_lshl_b64 s[2:3], s[78:79], 9
	v_ashrrev_i32_e32 v3, 31, v2
	v_lshl_add_u64 v[4:5], s[2:3], 0, v[2:3]
	s_mov_b64 s[2:3], 0x410000
	v_writelane_b32 v252, s48, 24
	v_cmp_gt_u64_e32 vcc, s[2:3], v[4:5]
	s_and_saveexec_b64 s[2:3], vcc
	s_cbranch_execz .LBB0_60
	s_load_dwordx2 s[12:13], s[74:75], 0x118
	s_waitcnt lgkmcnt(0)
	s_mov_b32 s13, s79
	v_lshlrev_b64 v[6:7], 5, v[2:3]
	s_mov_b64 s[16:17], 0x400000
	s_mov_b64 s[18:19], 0x40ffff
	s_lshl_b64 s[8:9], s[12:13], 9
	s_add_u32 s6, s6, 0xf8000000
	s_addc_u32 s7, s7, -1
	s_lshl_b64 s[10:11], s[78:79], 14
	v_lshl_add_u64 v[6:7], s[10:11], 0, v[6:7]
	s_lshl_b64 s[10:11], s[12:13], 14
	s_lshl_b64 s[14:15], s[78:79], 13
	s_add_u32 s14, s46, s14
	s_addc_u32 s15, s47, s15
	v_lshl_add_u64 v[2:3], v[2:3], 4, s[14:15]
	s_mov_b64 s[14:15], 0x4000000
	v_lshl_add_u64 v[2:3], v[2:3], 0, s[14:15]
	s_lshl_b64 s[12:13], s[12:13], 13
	s_mov_b64 s[14:15], 0
	s_mov_b32 s100, 8
.Lx2b_loop:
	v_lshl_add_u64 v[100:101], s[4:5], 0, v[6:7]
	v_lshl_add_u64 v[102:103], v[100:101], 0, s[10:11]
	v_lshl_add_u64 v[104:105], v[102:103], 0, s[10:11]
	v_lshl_add_u64 v[106:107], v[104:105], 0, s[10:11]
	global_load_dwordx4 v[108:111], v[100:101], off
	global_load_dwordx4 v[112:115], v[100:101], off offset:16
	global_load_dwordx4 v[116:119], v[102:103], off
	global_load_dwordx4 v[120:123], v[102:103], off offset:16
	global_load_dwordx4 v[124:127], v[104:105], off
	global_load_dwordx4 v[128:131], v[104:105], off offset:16
	global_load_dwordx4 v[132:135], v[106:107], off
	global_load_dwordx4 v[136:139], v[106:107], off offset:16
	v_lshl_add_u64 v[140:141], v[2:3], 0, s[12:13]
	v_lshl_add_u64 v[142:143], v[140:141], 0, s[12:13]
	v_lshl_add_u64 v[144:145], v[142:143], 0, s[12:13]
	s_waitcnt vmcnt(6)
	v_cvt_pk_bf16_f32 v108, v108, v109
	v_cvt_pk_bf16_f32 v109, v110, v111
	v_cvt_pk_bf16_f32 v110, v112, v113
	v_cvt_pk_bf16_f32 v111, v114, v115
	global_store_dwordx4 v[2:3], v[108:111], off
	s_waitcnt vmcnt(5)
	v_cvt_pk_bf16_f32 v116, v116, v117
	v_cvt_pk_bf16_f32 v117, v118, v119
	v_cvt_pk_bf16_f32 v118, v120, v121
	v_cvt_pk_bf16_f32 v119, v122, v123
	global_store_dwordx4 v[140:141], v[116:119], off
	s_waitcnt vmcnt(4)
	v_cvt_pk_bf16_f32 v124, v124, v125
	v_cvt_pk_bf16_f32 v125, v126, v127
	v_cvt_pk_bf16_f32 v126, v128, v129
	v_cvt_pk_bf16_f32 v127, v130, v131
	global_store_dwordx4 v[142:143], v[124:127], off
	s_waitcnt vmcnt(3)
	v_cvt_pk_bf16_f32 v132, v132, v133
	v_cvt_pk_bf16_f32 v133, v134, v135
	v_cvt_pk_bf16_f32 v134, v136, v137
	v_cvt_pk_bf16_f32 v135, v138, v139
	global_store_dwordx4 v[144:145], v[132:135], off
	v_lshl_add_u64 v[2:3], v[144:145], 0, s[12:13]
	v_lshl_add_u64 v[6:7], v[6:7], 0, s[10:11]
	v_lshl_add_u64 v[6:7], v[6:7], 0, s[10:11]
	v_lshl_add_u64 v[6:7], v[6:7], 0, s[10:11]
	v_lshl_add_u64 v[6:7], v[6:7], 0, s[10:11]
	v_lshl_add_u64 v[4:5], v[4:5], 0, s[8:9]
	v_lshl_add_u64 v[4:5], v[4:5], 0, s[8:9]
	v_lshl_add_u64 v[4:5], v[4:5], 0, s[8:9]
	v_lshl_add_u64 v[4:5], v[4:5], 0, s[8:9]
	s_sub_u32 s100, s100, 1
	s_cmp_lg_u32 s100, 0
	s_cbranch_scc1 .Lx2b_loop
	s_mov_b64 s[100:101], 0x410000
	v_cmp_gt_u64_e32 vcc, s[100:101], v[4:5]
	s_and_b64 exec, exec, vcc
	s_cbranch_execz .LBB0_60
